# whole gated merge GEMM now done by the hand-written 64x128 tile loop with 4 per-branch accumulators (each gate read once, no mid-K rescale hooks); K order rotated per workgroup in the ctx slivers
# speedup vs baseline: 1.0300x; 1.0077x over previous
.LBB0_1165:
	v_mov_b32_e32 v0, s15
	v_mov_b32_e32 v2, s14
	s_cmp_gt_i32 s87, 3
	v_readfirstlane_b32 s14, v2
	v_readlane_b32 s22, v254, 56
	v_mov_b32_e32 v2, s12
	v_writelane_b32 v255, s14, 10
	v_readfirstlane_b32 s14, v0
	v_mov_b32_e32 v0, s13
	s_cselect_b64 s[20:21], -1, 0
	v_readlane_b32 s23, v254, 57
	v_writelane_b32 v255, s14, 11
	s_and_b64 s[20:21], s[22:23], s[20:21]
	v_readfirstlane_b32 s12, v2
	v_mov_b32_e32 v2, s8
	s_and_b64 s[20:21], s[20:21], exec
	v_writelane_b32 v255, s12, 12
	v_readfirstlane_b32 s12, v0
	v_mov_b32_e32 v0, s9
	s_cselect_b32 s81, 64, 0x48
	s_bitcmp1_b32 s87, 0
	s_cselect_b32 s81, 64, s81
	s_cmp_eq_u32 s87, 4
	s_cselect_b32 s81, 0, s81
	v_writelane_b32 v255, s12, 13
	v_readfirstlane_b32 s8, v2
	v_mov_b32_e32 v2, s40
	s_lshr_b32 s91, s1, 8
	v_writelane_b32 v255, s8, 14
	v_readfirstlane_b32 s8, v0
	v_mov_b32_e32 v0, s41
	s_cmpk_eq_i32 s1, 0x1800
	v_writelane_b32 v255, s8, 15
	v_readfirstlane_b32 s8, v2
	s_cselect_b64 s[14:15], -1, 0
	s_mul_i32 s46, s91, s81
	v_writelane_b32 v255, s8, 16
	v_readfirstlane_b32 s8, v0
	v_mov_b32_e32 v0, s88
	v_mov_b32_e32 v14, v247
	v_writelane_b32 v255, s8, 17
	s_and_b64 s[8:9], s[14:15], exec
	s_cselect_b32 s12, 8, 4
	s_cmpk_eq_i32 s4, 0xb00
	s_cselect_b64 s[22:23], -1, 0
	s_and_b64 s[8:9], s[22:23], exec
	s_cselect_b32 s12, 2, s12
	s_cmpk_eq_i32 s1, 0x1600
	s_cselect_b64 s[24:25], -1, 0
	v_readfirstlane_b32 s90, v0
	s_and_b64 s[8:9], s[24:25], exec
	s_cselect_b32 s92, 4, s12
	s_cmp_lt_i32 s90, s46
	s_mul_i32 s38, s78, s79
	s_cselect_b64 s[12:13], -1, 0
	s_cmp_ge_i32 s90, s46
	v_readfirstlane_b32 s20, v14
	s_cbranch_scc0 .LBB0_1223
	s_sub_u32 s28, s90, s46
	s_subb_u32 s29, 0, 0
	v_mov_b32_e32 v0, s38
	v_cmp_lt_i64_e32 vcc, s[28:29], v[0:1]
	s_mov_b64 s[8:9], 0
	s_and_b64 vcc, exec, vcc
	s_mov_b64 s[26:27], 0
	s_cbranch_vccz .LBB0_1168
	s_sext_i32_i16 s18, s28
	s_bfe_u32 s18, s18, 0x3001c
	s_add_i32 s18, s28, s18
	s_sext_i32_i16 s21, s18
	s_and_b32 s18, s18, 0xfff8
	s_sub_i32 s18, s28, s18
	s_lshr_b32 s1, s38, 3
	s_ashr_i32 s21, s21, 3
	s_bfe_u32 s28, s18, 0x1000f
	s_and_b64 s[26:27], s[14:15], exec
	s_cselect_b32 s29, 3, 2
	s_and_b64 s[26:27], s[22:23], exec
	s_cselect_b32 s29, 1, s29
	s_and_b64 s[26:27], s[24:25], exec
	s_cselect_b32 s29, 2, s29
	s_lshl_b32 s30, s78, s29
	s_or_b32 s1, s28, s1
	s_mul_i32 s1, s1, s18
	s_sext_i32_i16 s18, s30
	v_cvt_f32_i32_e32 v0, s18
	s_add_i32 s1, s1, s21
	s_sext_i32_i16 s21, s1
	v_cvt_f32_i32_e32 v2, s21
	v_rcp_iflag_f32_e32 v3, v0
	s_xor_b32 s18, s21, s18
	s_ashr_i32 s18, s18, 30
	s_or_b32 s18, s18, 1
	v_mul_f32_e32 v3, v2, v3
	v_trunc_f32_e32 v3, v3
	v_fma_f32 v2, -v3, v0, v2
	v_cvt_i32_f32_e32 v3, v3
	v_cmp_ge_f32_e64 s[26:27], |v2|, |v0|
	s_and_b64 s[26:27], s[26:27], exec
	s_cselect_b32 s18, s18, 0
	v_readfirstlane_b32 s21, v3
	s_add_i32 s26, s21, s18
	s_sext_i32_i16 s18, s26
	s_lshl_b32 s18, s18, s29
	s_sub_i32 s21, s79, s18
	s_mul_i32 s26, s26, s30
	s_mov_b32 s94, 1
	s_min_i32 s21, s21, s92
	s_sub_i32 s29, s1, s26
	s_mov_b64 s[26:27], -1
	s_and_b64 vcc, exec, s[8:9]
	s_cbranch_vccz .LBB0_1170
	s_branch .LBB0_1169

.Lsl_par5:
	s_mov_b32 s45, 16
	s_movk_i32 s43, 0x800
	s_add_u32 s4, s10, 0x9b00000
	s_addc_u32 s5, s11, 0
	s_add_u32 s6, s10, 0x2080000
	s_addc_u32 s7, s11, 0
	s_mov_b32 s42, 1.0
	s_mov_b32 s46, 0x5000
	s_cmp_eq_u32 s87, 5
	s_cbranch_scc1 .Lsl_par_done
	s_add_u32 s4, s10, 0x1e300000
	s_addc_u32 s5, s11, 0
	s_add_u32 s6, s10, 0x1e80000
	s_addc_u32 s7, s11, 0
.Lsl_par_done:
	s_add_u32 s34, s10, 0x7300000
	s_addc_u32 s35, s11, 0
	v_readlane_b32 s47, v254, 38
	s_mul_i32 s47, s47, 0x51000
	s_add_u32 s47, s47, 0x48000
	s_add_u32 s47, s47, s46
	s_add_u32 s40, s10, 0x20700000
	s_addc_u32 s41, s11, 0
	s_add_u32 s40, s40, s47
	s_addc_u32 s41, s41, 0
	s_and_b32 s46, s88, 7
	s_lshr_b32 s47, s88, 3
	s_and_b32 s48, s46, 1
	s_lshl_b32 s48, s48, 2
	s_and_b32 s49, s47, 3
	s_add_u32 s48, s48, s49
	s_lshr_b32 s49, s46, 1
	s_lshl_b32 s49, s49, 3
	s_lshr_b32 s50, s47, 2
	s_add_u32 s49, s49, s50
	v_and_b32_e32 v71, 63, v247
	v_lshrrev_b32_e32 v72, 6, v247
	v_lshrrev_b32_e32 v73, 4, v71
	v_and_b32_e32 v73, 2, v73
	v_xor_b32_e32 v73, v73, v71
	v_readfirstlane_b32 s21, v72
	v_lshrrev_b32_e32 v74, 2, v73
	v_and_b32_e32 v75, 3, v73
	v_lshlrev_b32_e32 v75, 4, v75
	s_lshr_b32 s50, s21, 1
	s_lshl_b32 s50, s50, 4
	s_lshl_b32 s51, s49, 6
	s_add_u32 s50, s50, s51
	s_and_b32 s51, s21, 1
	s_lshl_b32 s51, s51, 6
	v_add_u32_e32 v64, s50, v74
	v_mul_lo_u32 v64, v64, s43
	v_add3_u32 v64, v64, v75, s51
	s_lshl_b32 s50, s48, 7
	s_lshl_b32 s51, s21, 4
	s_add_u32 s50, s50, s51
	v_add_u32_e32 v65, s50, v74
	v_mul_lo_u32 v65, v65, s43
	v_add_u32_e32 v65, v65, v75
	v_add_u32_e32 v66, 64, v65
	v_and_b32_e32 v73, 15, v71
	v_lshrrev_b32_e32 v74, 4, v71
	v_lshlrev_b32_e32 v75, 6, v73
	v_lshl_add_u32 v75, v74, 4, v75
	v_lshrrev_b32_e32 v72, 3, v73
	v_lshlrev_b32_e32 v72, 5, v72
	v_xor_b32_e32 v75, v75, v72
	s_lshr_b32 s50, s21, 2
	s_and_b32 s51, s21, 3
	s_lshl_b32 s52, s50, 12
	s_add_u32 s52, s52, 16
	v_add_u32_e32 v67, s52, v75
	s_lshl_b32 s52, s51, 12
	s_add_u32 s52, s52, 0x2010
	v_add_u32_e32 v68, s52, v75
	v_add_u32_e32 v69, 0xc000, v67
	v_add_u32_e32 v70, 0xc000, v68
	s_lshl_b32 s32, s21, 10
	s_add_u32 s32, s32, 16
	s_lshl_b32 s33, s21, 11
	s_add_u32 s33, s33, 0x2010
	s_lshl_b32 s52, s49, 6
	s_lshl_b32 s56, s50, 5
	s_add_u32 s52, s52, s56
	v_add_u32_e32 v71, s52, v73
	s_lshl_b32 s52, s48, 7
	s_lshl_b32 s56, s51, 5
	s_add_u32 s52, s52, s56
	v_lshl_add_u32 v72, v74, 2, s52
	v_lshl_add_u32 v100, v71, 10, v72
	v_lshlrev_b32_e32 v100, 2, v100
	v_lshlrev_b32_e32 v102, 2, v72
	v_add_u32_e32 v101, 0x10000, v100
	v_mov_b32_e32 v202, v102
	v_lshl_add_u32 v203, v71, 10, v72
	v_lshlrev_b32_e32 v203, 1, v203
	v_add_u32_e32 v204, 0x8000, v203
	v_mul_u32_u24_e32 v200, 0x3000, v71
	v_lshl_add_u32 v200, v72, 1, v200
	v_add_u32_e32 v201, 0x30000, v200
	s_cmp_eq_u32 s87, 4
	s_cbranch_scc1 .Lsb_start
	v_mov_b32_e32 v16, 0
	v_mov_b32_e32 v17, 0
	v_mov_b32_e32 v18, 0
	v_mov_b32_e32 v19, 0
	v_mov_b32_e32 v20, 0
	v_mov_b32_e32 v21, 0
	v_mov_b32_e32 v22, 0
	v_mov_b32_e32 v23, 0
	v_mov_b32_e32 v24, 0
	v_mov_b32_e32 v25, 0
	v_mov_b32_e32 v26, 0
	v_mov_b32_e32 v27, 0
	v_mov_b32_e32 v28, 0
	v_mov_b32_e32 v29, 0
	v_mov_b32_e32 v30, 0
	v_mov_b32_e32 v31, 0
	s_mov_b32 s14, s45
	s_lshr_b32 s90, s88, 3
	s_mul_i32 s90, s90, 7
	s_cmp_eq_u32 s45, 16
	s_cbranch_scc1 .Lsl_rot16
	s_mul_hi_u32 s89, s90, 0x5d1745e
	s_mul_i32 s89, s89, 44
	s_sub_u32 s90, s90, s89
	s_branch .Lsl_rot_done
.Lsl_rot16:
	s_and_b32 s90, s90, 15
.Lsl_rot_done:
	s_sub_u32 s89, s45, s90
	s_lshl_b32 s90, s90, 7
	s_add_u32 s4, s4, s90
	s_addc_u32 s5, s5, 0
	s_add_u32 s6, s6, s90
	s_addc_u32 s7, s7, 0
	s_lshl_b32 s90, s45, 7
	s_add_i32 m0, s32, 0
	s_nop 0
	global_load_lds_dwordx4 v64, s[4:5]
	s_add_i32 m0, s33, 0
	s_nop 0
	global_load_lds_dwordx4 v65, s[6:7]
	s_add_i32 m0, s33, 1024
	s_nop 0
	global_load_lds_dwordx4 v66, s[6:7]
	s_add_u32 s4, s4, 0x80
	s_addc_u32 s5, s5, 0
	s_add_u32 s6, s6, 0x80
	s_addc_u32 s7, s7, 0
	s_sub_u32 s89, s89, 1
	s_cmp_eq_u32 s89, 0
	s_cbranch_scc0 .Lsl_nowrap1
	s_sub_u32 s4, s4, s90
	s_subb_u32 s5, s5, 0
	s_sub_u32 s6, s6, s90
	s_subb_u32 s7, s7, 0
.Lsl_nowrap1:
	s_add_i32 m0, s32, 24576
	s_nop 0
	global_load_lds_dwordx4 v64, s[4:5]
	s_add_i32 m0, s33, 24576
	s_nop 0
	global_load_lds_dwordx4 v65, s[6:7]
	s_add_i32 m0, s33, 25600
	s_nop 0
	global_load_lds_dwordx4 v66, s[6:7]
	s_add_u32 s4, s4, 0x80
	s_addc_u32 s5, s5, 0
	s_add_u32 s6, s6, 0x80
	s_addc_u32 s7, s7, 0
	s_sub_u32 s89, s89, 1
	s_cmp_eq_u32 s89, 0
	s_cbranch_scc0 .Lsl_nowrap2
	s_sub_u32 s4, s4, s90
	s_subb_u32 s5, s5, 0
	s_sub_u32 s6, s6, s90
	s_subb_u32 s7, s7, 0
.Lsl_nowrap2:
	s_add_i32 m0, s32, 49152
	s_nop 0
	global_load_lds_dwordx4 v64, s[4:5]
	s_add_i32 m0, s33, 49152
	s_nop 0
	global_load_lds_dwordx4 v65, s[6:7]
	s_add_i32 m0, s33, 50176
	s_nop 0
	global_load_lds_dwordx4 v66, s[6:7]
	s_add_u32 s4, s4, 0x80
	s_addc_u32 s5, s5, 0
	s_add_u32 s6, s6, 0x80
	s_addc_u32 s7, s7, 0
	s_sub_u32 s89, s89, 1
	s_cmp_eq_u32 s89, 0
	s_cbranch_scc0 .Lsl_nowrap3
	s_sub_u32 s4, s4, s90
	s_subb_u32 s5, s5, 0
	s_sub_u32 s6, s6, s90
	s_subb_u32 s7, s7, 0
.Lsl_nowrap3:
.Lsl_loop:
	s_cmp_lt_u32 s14, 3
	s_cbranch_scc1 .Lsl_tail0
	s_waitcnt vmcnt(6)
	s_barrier
	s_cmp_lt_u32 s14, 4
	s_cbranch_scc1 .Lsl_go0
	s_add_i32 m0, s32, 73728
	s_nop 0
	global_load_lds_dwordx4 v64, s[4:5]
	s_add_i32 m0, s33, 73728
	s_nop 0
	global_load_lds_dwordx4 v65, s[6:7]
	s_add_i32 m0, s33, 74752
	s_nop 0
	global_load_lds_dwordx4 v66, s[6:7]
	s_add_u32 s4, s4, 0x80
	s_addc_u32 s5, s5, 0
	s_add_u32 s6, s6, 0x80
	s_addc_u32 s7, s7, 0
	s_sub_u32 s89, s89, 1
	s_cmp_eq_u32 s89, 0
	s_cbranch_scc0 .Lsl_nowrap4
	s_sub_u32 s4, s4, s90
	s_subb_u32 s5, s5, 0
	s_sub_u32 s6, s6, s90
	s_subb_u32 s7, s7, 0
.Lsl_nowrap4:
	s_branch .Lsl_go0
.Lsl_tail0:
	s_waitcnt vmcnt(0)
	s_barrier
.Lsl_go0:
	ds_read_b128 v[48:51], v68 offset:0
	ds_read_b128 v[56:59], v68 offset:2048
	ds_read_b128 v[32:35], v67 offset:0
	ds_read_b128 v[40:43], v67 offset:2048
	ds_read_b128 v[52:55], v68 offset:1024
	ds_read_b128 v[60:63], v68 offset:3072
	ds_read_b128 v[36:39], v67 offset:1024
	ds_read_b128 v[44:47], v67 offset:3072
	s_waitcnt lgkmcnt(4)
	v_mfma_f32_16x16x32_bf16 v[16:19], v[48:51], v[32:35], v[16:19]
	v_mfma_f32_16x16x32_bf16 v[20:23], v[56:59], v[32:35], v[20:23]
	v_mfma_f32_16x16x32_bf16 v[24:27], v[48:51], v[40:43], v[24:27]
	v_mfma_f32_16x16x32_bf16 v[28:31], v[56:59], v[40:43], v[28:31]
	s_waitcnt lgkmcnt(0)
	v_mfma_f32_16x16x32_bf16 v[16:19], v[52:55], v[36:39], v[16:19]
	v_mfma_f32_16x16x32_bf16 v[20:23], v[60:63], v[36:39], v[20:23]
	v_mfma_f32_16x16x32_bf16 v[24:27], v[52:55], v[44:47], v[24:27]
	v_mfma_f32_16x16x32_bf16 v[28:31], v[60:63], v[44:47], v[28:31]
	s_sub_u32 s14, s14, 1
	s_cmp_lt_u32 s14, 3
	s_cbranch_scc1 .Lsl_tail1
	s_waitcnt vmcnt(6)
	s_barrier
	s_cmp_lt_u32 s14, 4
	s_cbranch_scc1 .Lsl_go1
	s_add_i32 m0, s32, 0
	s_nop 0
	global_load_lds_dwordx4 v64, s[4:5]
	s_add_i32 m0, s33, 0
	s_nop 0
	global_load_lds_dwordx4 v65, s[6:7]
	s_add_i32 m0, s33, 1024
	s_nop 0
	global_load_lds_dwordx4 v66, s[6:7]
	s_add_u32 s4, s4, 0x80
	s_addc_u32 s5, s5, 0
	s_add_u32 s6, s6, 0x80
	s_addc_u32 s7, s7, 0
	s_sub_u32 s89, s89, 1
	s_cmp_eq_u32 s89, 0
	s_cbranch_scc0 .Lsl_nowrap5
	s_sub_u32 s4, s4, s90
	s_subb_u32 s5, s5, 0
	s_sub_u32 s6, s6, s90
	s_subb_u32 s7, s7, 0
.Lsl_nowrap5:
	s_branch .Lsl_go1
.Lsl_tail1:
	s_waitcnt vmcnt(0)
	s_barrier
.Lsl_go1:
	ds_read_b128 v[48:51], v68 offset:24576
	ds_read_b128 v[56:59], v68 offset:26624
	ds_read_b128 v[32:35], v67 offset:24576
	ds_read_b128 v[40:43], v67 offset:26624
	ds_read_b128 v[52:55], v68 offset:25600
	ds_read_b128 v[60:63], v68 offset:27648
	ds_read_b128 v[36:39], v67 offset:25600
	ds_read_b128 v[44:47], v67 offset:27648
	s_waitcnt lgkmcnt(4)
	v_mfma_f32_16x16x32_bf16 v[16:19], v[48:51], v[32:35], v[16:19]
	v_mfma_f32_16x16x32_bf16 v[20:23], v[56:59], v[32:35], v[20:23]
	v_mfma_f32_16x16x32_bf16 v[24:27], v[48:51], v[40:43], v[24:27]
	v_mfma_f32_16x16x32_bf16 v[28:31], v[56:59], v[40:43], v[28:31]
	s_waitcnt lgkmcnt(0)
	v_mfma_f32_16x16x32_bf16 v[16:19], v[52:55], v[36:39], v[16:19]
	v_mfma_f32_16x16x32_bf16 v[20:23], v[60:63], v[36:39], v[20:23]
	v_mfma_f32_16x16x32_bf16 v[24:27], v[52:55], v[44:47], v[24:27]
	v_mfma_f32_16x16x32_bf16 v[28:31], v[60:63], v[44:47], v[28:31]
	s_sub_u32 s14, s14, 1
	s_cmp_lt_u32 s14, 3
	s_cbranch_scc1 .Lsl_tail2
	s_waitcnt vmcnt(6)
	s_barrier
	s_cmp_lt_u32 s14, 4
	s_cbranch_scc1 .Lsl_go2
	s_add_i32 m0, s32, 24576
	s_nop 0
	global_load_lds_dwordx4 v64, s[4:5]
	s_add_i32 m0, s33, 24576
	s_nop 0
	global_load_lds_dwordx4 v65, s[6:7]
	s_add_i32 m0, s33, 25600
	s_nop 0
	global_load_lds_dwordx4 v66, s[6:7]
	s_add_u32 s4, s4, 0x80
	s_addc_u32 s5, s5, 0
	s_add_u32 s6, s6, 0x80
	s_addc_u32 s7, s7, 0
	s_sub_u32 s89, s89, 1
	s_cmp_eq_u32 s89, 0
	s_cbranch_scc0 .Lsl_nowrap6
	s_sub_u32 s4, s4, s90
	s_subb_u32 s5, s5, 0
	s_sub_u32 s6, s6, s90
	s_subb_u32 s7, s7, 0
.Lsl_nowrap6:
	s_branch .Lsl_go2
.Lsl_tail2:
	s_waitcnt vmcnt(0)
	s_barrier
.Lsl_go2:
	ds_read_b128 v[48:51], v70 offset:0
	ds_read_b128 v[56:59], v70 offset:2048
	ds_read_b128 v[32:35], v69 offset:0
	ds_read_b128 v[40:43], v69 offset:2048
	ds_read_b128 v[52:55], v70 offset:1024
	ds_read_b128 v[60:63], v70 offset:3072
	ds_read_b128 v[36:39], v69 offset:1024
	ds_read_b128 v[44:47], v69 offset:3072
	s_waitcnt lgkmcnt(4)
	v_mfma_f32_16x16x32_bf16 v[16:19], v[48:51], v[32:35], v[16:19]
	v_mfma_f32_16x16x32_bf16 v[20:23], v[56:59], v[32:35], v[20:23]
	v_mfma_f32_16x16x32_bf16 v[24:27], v[48:51], v[40:43], v[24:27]
	v_mfma_f32_16x16x32_bf16 v[28:31], v[56:59], v[40:43], v[28:31]
	s_waitcnt lgkmcnt(0)
	v_mfma_f32_16x16x32_bf16 v[16:19], v[52:55], v[36:39], v[16:19]
	v_mfma_f32_16x16x32_bf16 v[20:23], v[60:63], v[36:39], v[20:23]
	v_mfma_f32_16x16x32_bf16 v[24:27], v[52:55], v[44:47], v[24:27]
	v_mfma_f32_16x16x32_bf16 v[28:31], v[60:63], v[44:47], v[28:31]
	s_sub_u32 s14, s14, 1
	s_cmp_lt_u32 s14, 3
	s_cbranch_scc1 .Lsl_tail3
	s_waitcnt vmcnt(6)
	s_barrier
	s_cmp_lt_u32 s14, 4
	s_cbranch_scc1 .Lsl_go3
	s_add_i32 m0, s32, 49152
	s_nop 0
	global_load_lds_dwordx4 v64, s[4:5]
	s_add_i32 m0, s33, 49152
	s_nop 0
	global_load_lds_dwordx4 v65, s[6:7]
	s_add_i32 m0, s33, 50176
	s_nop 0
	global_load_lds_dwordx4 v66, s[6:7]
	s_add_u32 s4, s4, 0x80
	s_addc_u32 s5, s5, 0
	s_add_u32 s6, s6, 0x80
	s_addc_u32 s7, s7, 0
	s_sub_u32 s89, s89, 1
	s_cmp_eq_u32 s89, 0
	s_cbranch_scc0 .Lsl_nowrap7
	s_sub_u32 s4, s4, s90
	s_subb_u32 s5, s5, 0
	s_sub_u32 s6, s6, s90
	s_subb_u32 s7, s7, 0
.Lsl_nowrap7:
	s_branch .Lsl_go3
.Lsl_tail3:
	s_waitcnt vmcnt(0)
	s_barrier

.Lsb_start:
	s_load_dwordx2 s[56:57], s[64:65], 0x60
	v_readlane_b32 s47, v254, 49
	s_cmp_eq_u32 s47, 0
	s_cselect_b32 s80, 8, 9
	s_mov_b32 s15, 0
	s_mov_b64 s[60:61], s[4:5]
	s_add_u32 s34, s10, 0x9f01000
	s_addc_u32 s35, s11, 0
	s_add_u32 s58, s10, 0x7b00000
	s_addc_u32 s59, s11, 0
	v_readlane_b32 s47, v254, 38
	s_lshl_b32 s47, s47, 14
	s_waitcnt lgkmcnt(0)
	s_add_u32 s56, s56, s47
	s_addc_u32 s57, s57, 0
	global_load_dwordx4 v[72:75], v202, s[56:57]
	global_load_dwordx4 v[76:79], v202, s[56:57] offset:64
	s_add_u32 s56, s56, 0x1000
	s_addc_u32 s57, s57, 0
	global_load_dwordx4 v[80:83], v202, s[56:57]
	global_load_dwordx4 v[84:87], v202, s[56:57] offset:64
	s_add_u32 s56, s56, 0x1000
	s_addc_u32 s57, s57, 0
	global_load_dwordx4 v[88:91], v202, s[56:57]
	global_load_dwordx4 v[92:95], v202, s[56:57] offset:64
	s_add_u32 s56, s56, 0x1000
	s_addc_u32 s57, s57, 0
	global_load_dwordx4 v[96:99], v202, s[56:57]
	global_load_dwordx4 v[100:103], v202, s[56:57] offset:64
.Lsb_tile:
	s_mov_b64 s[4:5], s[60:61]
	s_add_u32 s6, s10, 0x1e80000
	s_addc_u32 s7, s11, 0
	s_add_u32 s40, s34, 0x1000
	s_addc_u32 s41, s35, 0
	v_mov_b32_e32 v16, 0
	v_mov_b32_e32 v17, 0
	v_mov_b32_e32 v18, 0
	v_mov_b32_e32 v19, 0
	v_mov_b32_e32 v20, 0
	v_mov_b32_e32 v21, 0
	v_mov_b32_e32 v22, 0
	v_mov_b32_e32 v23, 0
	v_mov_b32_e32 v24, 0
	v_mov_b32_e32 v25, 0
	v_mov_b32_e32 v26, 0
	v_mov_b32_e32 v27, 0
	v_mov_b32_e32 v28, 0
	v_mov_b32_e32 v29, 0
	v_mov_b32_e32 v30, 0
	v_mov_b32_e32 v31, 0
	v_mov_b32_e32 v104, 0
	v_mov_b32_e32 v105, 0
	v_mov_b32_e32 v106, 0
	v_mov_b32_e32 v107, 0
	v_mov_b32_e32 v108, 0
	v_mov_b32_e32 v109, 0
	v_mov_b32_e32 v110, 0
	v_mov_b32_e32 v111, 0
	v_mov_b32_e32 v112, 0
	v_mov_b32_e32 v113, 0
	v_mov_b32_e32 v114, 0
	v_mov_b32_e32 v115, 0
	v_mov_b32_e32 v116, 0
	v_mov_b32_e32 v117, 0
	v_mov_b32_e32 v118, 0
	v_mov_b32_e32 v119, 0
	v_mov_b32_e32 v120, 0
	v_mov_b32_e32 v121, 0
	v_mov_b32_e32 v122, 0
	v_mov_b32_e32 v123, 0
	v_mov_b32_e32 v124, 0
	v_mov_b32_e32 v125, 0
	v_mov_b32_e32 v126, 0
	v_mov_b32_e32 v127, 0
	v_mov_b32_e32 v128, 0
	v_mov_b32_e32 v129, 0
	v_mov_b32_e32 v130, 0
	v_mov_b32_e32 v131, 0
	v_mov_b32_e32 v132, 0
	v_mov_b32_e32 v133, 0
	v_mov_b32_e32 v134, 0
	v_mov_b32_e32 v135, 0
	v_mov_b32_e32 v136, 0
	v_mov_b32_e32 v137, 0
	v_mov_b32_e32 v138, 0
	v_mov_b32_e32 v139, 0
	v_mov_b32_e32 v140, 0
	v_mov_b32_e32 v141, 0
	v_mov_b32_e32 v142, 0
	v_mov_b32_e32 v143, 0
	v_mov_b32_e32 v144, 0
	v_mov_b32_e32 v145, 0
	v_mov_b32_e32 v146, 0
	v_mov_b32_e32 v147, 0
	v_mov_b32_e32 v148, 0
	v_mov_b32_e32 v149, 0
	v_mov_b32_e32 v150, 0
	v_mov_b32_e32 v151, 0
	s_add_i32 m0, s32, 0
	s_nop 0
	global_load_lds_dwordx4 v64, s[4:5]
	s_add_i32 m0, s33, 0
	s_nop 0
	global_load_lds_dwordx4 v65, s[6:7]
	s_add_i32 m0, s33, 1024
	s_nop 0
	global_load_lds_dwordx4 v66, s[6:7]
	s_add_u32 s4, s4, 0x80
	s_addc_u32 s5, s5, 0
	s_add_u32 s6, s6, 0x80
	s_addc_u32 s7, s7, 0
	s_add_i32 m0, s32, 24576
	s_nop 0
	global_load_lds_dwordx4 v64, s[4:5]
	s_add_i32 m0, s33, 24576
	s_nop 0
	global_load_lds_dwordx4 v65, s[6:7]
	s_add_i32 m0, s33, 25600
	s_nop 0
	global_load_lds_dwordx4 v66, s[6:7]
	s_add_u32 s4, s4, 0x80
	s_addc_u32 s5, s5, 0
	s_add_u32 s6, s6, 0x80
	s_addc_u32 s7, s7, 0
	s_add_i32 m0, s32, 49152
	s_nop 0
	global_load_lds_dwordx4 v64, s[4:5]
	s_add_i32 m0, s33, 49152
	s_nop 0
	global_load_lds_dwordx4 v65, s[6:7]
	s_add_i32 m0, s33, 50176
	s_nop 0
	global_load_lds_dwordx4 v66, s[6:7]
	s_add_u32 s4, s4, 0x80
	s_addc_u32 s5, s5, 0
	s_add_u32 s6, s6, 0x80
	s_addc_u32 s7, s7, 0
	global_load_dwordx2 v[168:169], v200, s[34:35] offset:0
	global_load_dwordx2 v[170:171], v200, s[34:35] offset:32
	global_load_dwordx2 v[172:173], v201, s[34:35] offset:0
	global_load_dwordx2 v[174:175], v201, s[34:35] offset:32
	global_load_dwordx2 v[176:177], v200, s[34:35] offset:2048
	global_load_dwordx2 v[178:179], v200, s[34:35] offset:2080
	global_load_dwordx2 v[180:181], v201, s[34:35] offset:2048
	global_load_dwordx2 v[182:183], v201, s[34:35] offset:2080
	global_load_dwordx2 v[184:185], v200, s[40:41] offset:0
	global_load_dwordx2 v[186:187], v200, s[40:41] offset:32
	global_load_dwordx2 v[188:189], v201, s[40:41] offset:0
	global_load_dwordx2 v[190:191], v201, s[40:41] offset:32
	global_load_dwordx2 v[192:193], v200, s[40:41] offset:2048
	global_load_dwordx2 v[194:195], v200, s[40:41] offset:2080
	global_load_dwordx2 v[196:197], v201, s[40:41] offset:2048
	global_load_dwordx2 v[198:199], v201, s[40:41] offset:2080
	s_waitcnt vmcnt(22)
	s_barrier
	s_add_i32 m0, s32, 73728
	s_nop 0
	global_load_lds_dwordx4 v64, s[4:5]
	s_add_i32 m0, s33, 73728
	s_nop 0
	global_load_lds_dwordx4 v65, s[6:7]
	s_add_i32 m0, s33, 74752
	s_nop 0
	global_load_lds_dwordx4 v66, s[6:7]
	s_add_u32 s4, s4, 0x80
	s_addc_u32 s5, s5, 0
	s_add_u32 s6, s6, 0x80
	s_addc_u32 s7, s7, 0
	ds_read_b128 v[48:51], v68 offset:0
	ds_read_b128 v[56:59], v68 offset:2048
	ds_read_b128 v[32:35], v67 offset:0
	ds_read_b128 v[40:43], v67 offset:2048
	ds_read_b128 v[52:55], v68 offset:1024
	ds_read_b128 v[60:63], v68 offset:3072
	ds_read_b128 v[36:39], v67 offset:1024
	ds_read_b128 v[44:47], v67 offset:3072
	s_waitcnt lgkmcnt(4)
	v_mfma_f32_16x16x32_bf16 v[16:19], v[48:51], v[32:35], v[16:19]
	v_mfma_f32_16x16x32_bf16 v[20:23], v[56:59], v[32:35], v[20:23]
	v_mfma_f32_16x16x32_bf16 v[24:27], v[48:51], v[40:43], v[24:27]
	v_mfma_f32_16x16x32_bf16 v[28:31], v[56:59], v[40:43], v[28:31]
	s_waitcnt lgkmcnt(0)
	v_mfma_f32_16x16x32_bf16 v[16:19], v[52:55], v[36:39], v[16:19]
	v_mfma_f32_16x16x32_bf16 v[20:23], v[60:63], v[36:39], v[20:23]
	v_mfma_f32_16x16x32_bf16 v[24:27], v[52:55], v[44:47], v[24:27]
	v_mfma_f32_16x16x32_bf16 v[28:31], v[60:63], v[44:47], v[28:31]
	s_waitcnt vmcnt(22)
	s_barrier
	s_add_i32 m0, s32, 0
	s_nop 0
	global_load_lds_dwordx4 v64, s[4:5]
	s_add_i32 m0, s33, 0
	s_nop 0
	global_load_lds_dwordx4 v65, s[6:7]
	s_add_i32 m0, s33, 1024
	s_nop 0
	global_load_lds_dwordx4 v66, s[6:7]
	s_add_u32 s4, s4, 0x80
	s_addc_u32 s5, s5, 0
	s_add_u32 s6, s6, 0x80
	s_addc_u32 s7, s7, 0
	ds_read_b128 v[48:51], v68 offset:24576
	ds_read_b128 v[56:59], v68 offset:26624
	ds_read_b128 v[32:35], v67 offset:24576
	ds_read_b128 v[40:43], v67 offset:26624
	ds_read_b128 v[52:55], v68 offset:25600
	ds_read_b128 v[60:63], v68 offset:27648
	ds_read_b128 v[36:39], v67 offset:25600
	ds_read_b128 v[44:47], v67 offset:27648
	s_waitcnt lgkmcnt(4)
	v_mfma_f32_16x16x32_bf16 v[16:19], v[48:51], v[32:35], v[16:19]
	v_mfma_f32_16x16x32_bf16 v[20:23], v[56:59], v[32:35], v[20:23]
	v_mfma_f32_16x16x32_bf16 v[24:27], v[48:51], v[40:43], v[24:27]
	v_mfma_f32_16x16x32_bf16 v[28:31], v[56:59], v[40:43], v[28:31]
	s_waitcnt lgkmcnt(0)
	v_mfma_f32_16x16x32_bf16 v[16:19], v[52:55], v[36:39], v[16:19]
	v_mfma_f32_16x16x32_bf16 v[20:23], v[60:63], v[36:39], v[20:23]
	v_mfma_f32_16x16x32_bf16 v[24:27], v[52:55], v[44:47], v[24:27]
	v_mfma_f32_16x16x32_bf16 v[28:31], v[60:63], v[44:47], v[28:31]
	s_waitcnt vmcnt(22)
	s_barrier
	s_add_i32 m0, s32, 24576
	s_nop 0
	global_load_lds_dwordx4 v64, s[4:5]
	s_add_i32 m0, s33, 24576
	s_nop 0
	global_load_lds_dwordx4 v65, s[6:7]
	s_add_i32 m0, s33, 25600
	s_nop 0
	global_load_lds_dwordx4 v66, s[6:7]
	s_add_u32 s4, s4, 0x80
	s_addc_u32 s5, s5, 0
	s_add_u32 s6, s6, 0x80
	s_addc_u32 s7, s7, 0
	ds_read_b128 v[48:51], v70 offset:0
	ds_read_b128 v[56:59], v70 offset:2048
	ds_read_b128 v[32:35], v69 offset:0
	ds_read_b128 v[40:43], v69 offset:2048
	ds_read_b128 v[52:55], v70 offset:1024
	ds_read_b128 v[60:63], v70 offset:3072
	ds_read_b128 v[36:39], v69 offset:1024
	ds_read_b128 v[44:47], v69 offset:3072
	s_waitcnt lgkmcnt(4)
	v_mfma_f32_16x16x32_bf16 v[16:19], v[48:51], v[32:35], v[16:19]
	v_mfma_f32_16x16x32_bf16 v[20:23], v[56:59], v[32:35], v[20:23]
	v_mfma_f32_16x16x32_bf16 v[24:27], v[48:51], v[40:43], v[24:27]
	v_mfma_f32_16x16x32_bf16 v[28:31], v[56:59], v[40:43], v[28:31]
	s_waitcnt lgkmcnt(0)
	v_mfma_f32_16x16x32_bf16 v[16:19], v[52:55], v[36:39], v[16:19]
	v_mfma_f32_16x16x32_bf16 v[20:23], v[60:63], v[36:39], v[20:23]
	v_mfma_f32_16x16x32_bf16 v[24:27], v[52:55], v[44:47], v[24:27]
	v_mfma_f32_16x16x32_bf16 v[28:31], v[60:63], v[44:47], v[28:31]
	s_waitcnt vmcnt(6)
	s_barrier
	s_add_i32 m0, s32, 49152
	s_nop 0
	global_load_lds_dwordx4 v64, s[4:5]
	s_add_i32 m0, s33, 49152
	s_nop 0
	global_load_lds_dwordx4 v65, s[6:7]
	s_add_i32 m0, s33, 50176
	s_nop 0
	global_load_lds_dwordx4 v66, s[6:7]
	s_add_u32 s4, s4, 0x80
	s_addc_u32 s5, s5, 0
	s_add_u32 s6, s6, 0x80
	s_addc_u32 s7, s7, 0
	ds_read_b128 v[48:51], v70 offset:24576
	ds_read_b128 v[56:59], v70 offset:26624
	ds_read_b128 v[32:35], v69 offset:24576
	ds_read_b128 v[40:43], v69 offset:26624
	ds_read_b128 v[52:55], v70 offset:25600
	ds_read_b128 v[60:63], v70 offset:27648
	ds_read_b128 v[36:39], v69 offset:25600
	ds_read_b128 v[44:47], v69 offset:27648
	s_waitcnt lgkmcnt(4)
	v_mfma_f32_16x16x32_bf16 v[16:19], v[48:51], v[32:35], v[16:19]
	v_mfma_f32_16x16x32_bf16 v[20:23], v[56:59], v[32:35], v[20:23]
	v_mfma_f32_16x16x32_bf16 v[24:27], v[48:51], v[40:43], v[24:27]
	v_mfma_f32_16x16x32_bf16 v[28:31], v[56:59], v[40:43], v[28:31]
	s_waitcnt lgkmcnt(0)
	v_mfma_f32_16x16x32_bf16 v[16:19], v[52:55], v[36:39], v[16:19]
	v_mfma_f32_16x16x32_bf16 v[20:23], v[60:63], v[36:39], v[20:23]
	v_mfma_f32_16x16x32_bf16 v[24:27], v[52:55], v[44:47], v[24:27]
	v_mfma_f32_16x16x32_bf16 v[28:31], v[60:63], v[44:47], v[28:31]
	s_waitcnt vmcnt(6)
	s_barrier
	s_add_i32 m0, s32, 73728
	s_nop 0
	global_load_lds_dwordx4 v64, s[4:5]
	s_add_i32 m0, s33, 73728
	s_nop 0
	global_load_lds_dwordx4 v65, s[6:7]
	s_add_i32 m0, s33, 74752
	s_nop 0
	global_load_lds_dwordx4 v66, s[6:7]
	s_add_u32 s4, s4, 0x80
	s_addc_u32 s5, s5, 0
	s_add_u32 s6, s6, 0x80
	s_addc_u32 s7, s7, 0
	ds_read_b128 v[48:51], v68 offset:0
	ds_read_b128 v[56:59], v68 offset:2048
	ds_read_b128 v[32:35], v67 offset:0
	ds_read_b128 v[40:43], v67 offset:2048
	ds_read_b128 v[52:55], v68 offset:1024
	ds_read_b128 v[60:63], v68 offset:3072
	ds_read_b128 v[36:39], v67 offset:1024
	ds_read_b128 v[44:47], v67 offset:3072
	s_waitcnt lgkmcnt(4)
	v_mfma_f32_16x16x32_bf16 v[104:107], v[48:51], v[32:35], v[104:107]
	v_mfma_f32_16x16x32_bf16 v[108:111], v[56:59], v[32:35], v[108:111]
	v_mfma_f32_16x16x32_bf16 v[112:115], v[48:51], v[40:43], v[112:115]
	v_mfma_f32_16x16x32_bf16 v[116:119], v[56:59], v[40:43], v[116:119]
	s_waitcnt lgkmcnt(0)
	v_mfma_f32_16x16x32_bf16 v[104:107], v[52:55], v[36:39], v[104:107]
	v_mfma_f32_16x16x32_bf16 v[108:111], v[60:63], v[36:39], v[108:111]
	v_mfma_f32_16x16x32_bf16 v[112:115], v[52:55], v[44:47], v[112:115]
	v_mfma_f32_16x16x32_bf16 v[116:119], v[60:63], v[44:47], v[116:119]
	s_waitcnt vmcnt(6)
	s_barrier
	s_add_i32 m0, s32, 0
	s_nop 0
	global_load_lds_dwordx4 v64, s[4:5]
	s_add_i32 m0, s33, 0
	s_nop 0
	global_load_lds_dwordx4 v65, s[6:7]
	s_add_i32 m0, s33, 1024
	s_nop 0
	global_load_lds_dwordx4 v66, s[6:7]
	s_add_u32 s4, s4, 0x80
	s_addc_u32 s5, s5, 0
	s_add_u32 s6, s6, 0x80
	s_addc_u32 s7, s7, 0
	ds_read_b128 v[48:51], v68 offset:24576
	ds_read_b128 v[56:59], v68 offset:26624
	ds_read_b128 v[32:35], v67 offset:24576
	ds_read_b128 v[40:43], v67 offset:26624
	ds_read_b128 v[52:55], v68 offset:25600
	ds_read_b128 v[60:63], v68 offset:27648
	ds_read_b128 v[36:39], v67 offset:25600
	ds_read_b128 v[44:47], v67 offset:27648
	s_waitcnt lgkmcnt(4)
	v_mfma_f32_16x16x32_bf16 v[104:107], v[48:51], v[32:35], v[104:107]
	v_mfma_f32_16x16x32_bf16 v[108:111], v[56:59], v[32:35], v[108:111]
	v_mfma_f32_16x16x32_bf16 v[112:115], v[48:51], v[40:43], v[112:115]
	v_mfma_f32_16x16x32_bf16 v[116:119], v[56:59], v[40:43], v[116:119]
	s_waitcnt lgkmcnt(0)
	v_mfma_f32_16x16x32_bf16 v[104:107], v[52:55], v[36:39], v[104:107]
	v_mfma_f32_16x16x32_bf16 v[108:111], v[60:63], v[36:39], v[108:111]
	v_mfma_f32_16x16x32_bf16 v[112:115], v[52:55], v[44:47], v[112:115]
	v_mfma_f32_16x16x32_bf16 v[116:119], v[60:63], v[44:47], v[116:119]
	s_waitcnt vmcnt(6)
	s_barrier
	s_add_i32 m0, s32, 24576
	s_nop 0
	global_load_lds_dwordx4 v64, s[4:5]
	s_add_i32 m0, s33, 24576
	s_nop 0
	global_load_lds_dwordx4 v65, s[6:7]
	s_add_i32 m0, s33, 25600
	s_nop 0
	global_load_lds_dwordx4 v66, s[6:7]
	s_add_u32 s4, s4, 0x80
	s_addc_u32 s5, s5, 0
	s_add_u32 s6, s6, 0x80
	s_addc_u32 s7, s7, 0
	ds_read_b128 v[48:51], v70 offset:0
	ds_read_b128 v[56:59], v70 offset:2048
	ds_read_b128 v[32:35], v69 offset:0
	ds_read_b128 v[40:43], v69 offset:2048
	ds_read_b128 v[52:55], v70 offset:1024
	ds_read_b128 v[60:63], v70 offset:3072
	ds_read_b128 v[36:39], v69 offset:1024
	ds_read_b128 v[44:47], v69 offset:3072
	s_waitcnt lgkmcnt(4)
	v_mfma_f32_16x16x32_bf16 v[104:107], v[48:51], v[32:35], v[104:107]
	v_mfma_f32_16x16x32_bf16 v[108:111], v[56:59], v[32:35], v[108:111]
	v_mfma_f32_16x16x32_bf16 v[112:115], v[48:51], v[40:43], v[112:115]
	v_mfma_f32_16x16x32_bf16 v[116:119], v[56:59], v[40:43], v[116:119]
	s_waitcnt lgkmcnt(0)
	v_mfma_f32_16x16x32_bf16 v[104:107], v[52:55], v[36:39], v[104:107]
	v_mfma_f32_16x16x32_bf16 v[108:111], v[60:63], v[36:39], v[108:111]
	v_mfma_f32_16x16x32_bf16 v[112:115], v[52:55], v[44:47], v[112:115]
	v_mfma_f32_16x16x32_bf16 v[116:119], v[60:63], v[44:47], v[116:119]
	s_waitcnt vmcnt(6)
	s_barrier
	s_add_i32 m0, s32, 49152
	s_nop 0
	global_load_lds_dwordx4 v64, s[4:5]
	s_add_i32 m0, s33, 49152
	s_nop 0
	global_load_lds_dwordx4 v65, s[6:7]
	s_add_i32 m0, s33, 50176
	s_nop 0
	global_load_lds_dwordx4 v66, s[6:7]
	s_add_u32 s4, s4, 0x80
	s_addc_u32 s5, s5, 0
	s_add_u32 s6, s6, 0x80
	s_addc_u32 s7, s7, 0
	ds_read_b128 v[48:51], v70 offset:24576
	ds_read_b128 v[56:59], v70 offset:26624
	ds_read_b128 v[32:35], v69 offset:24576
	ds_read_b128 v[40:43], v69 offset:26624
	ds_read_b128 v[52:55], v70 offset:25600
	ds_read_b128 v[60:63], v70 offset:27648
	ds_read_b128 v[36:39], v69 offset:25600
	ds_read_b128 v[44:47], v69 offset:27648
	s_waitcnt lgkmcnt(4)
	v_mfma_f32_16x16x32_bf16 v[104:107], v[48:51], v[32:35], v[104:107]
	v_mfma_f32_16x16x32_bf16 v[108:111], v[56:59], v[32:35], v[108:111]
	v_mfma_f32_16x16x32_bf16 v[112:115], v[48:51], v[40:43], v[112:115]
	v_mfma_f32_16x16x32_bf16 v[116:119], v[56:59], v[40:43], v[116:119]
	s_waitcnt lgkmcnt(0)
	v_mfma_f32_16x16x32_bf16 v[104:107], v[52:55], v[36:39], v[104:107]
	v_mfma_f32_16x16x32_bf16 v[108:111], v[60:63], v[36:39], v[108:111]
	v_mfma_f32_16x16x32_bf16 v[112:115], v[52:55], v[44:47], v[112:115]
	v_mfma_f32_16x16x32_bf16 v[116:119], v[60:63], v[44:47], v[116:119]
	s_waitcnt vmcnt(6)
	s_barrier
	s_add_i32 m0, s32, 73728
	s_nop 0
	global_load_lds_dwordx4 v64, s[4:5]
	s_add_i32 m0, s33, 73728
	s_nop 0
	global_load_lds_dwordx4 v65, s[6:7]
	s_add_i32 m0, s33, 74752
	s_nop 0
	global_load_lds_dwordx4 v66, s[6:7]
	s_add_u32 s4, s4, 0x80
	s_addc_u32 s5, s5, 0
	s_add_u32 s6, s6, 0x80
	s_addc_u32 s7, s7, 0
	ds_read_b128 v[48:51], v68 offset:0
	ds_read_b128 v[56:59], v68 offset:2048
	ds_read_b128 v[32:35], v67 offset:0
	ds_read_b128 v[40:43], v67 offset:2048
	ds_read_b128 v[52:55], v68 offset:1024
	ds_read_b128 v[60:63], v68 offset:3072
	ds_read_b128 v[36:39], v67 offset:1024
	ds_read_b128 v[44:47], v67 offset:3072
	s_waitcnt lgkmcnt(4)
	v_mfma_f32_16x16x32_bf16 v[120:123], v[48:51], v[32:35], v[120:123]
	v_mfma_f32_16x16x32_bf16 v[124:127], v[56:59], v[32:35], v[124:127]
	v_mfma_f32_16x16x32_bf16 v[128:131], v[48:51], v[40:43], v[128:131]
	v_mfma_f32_16x16x32_bf16 v[132:135], v[56:59], v[40:43], v[132:135]
	s_waitcnt lgkmcnt(0)
	v_mfma_f32_16x16x32_bf16 v[120:123], v[52:55], v[36:39], v[120:123]
	v_mfma_f32_16x16x32_bf16 v[124:127], v[60:63], v[36:39], v[124:127]
	v_mfma_f32_16x16x32_bf16 v[128:131], v[52:55], v[44:47], v[128:131]
	v_mfma_f32_16x16x32_bf16 v[132:135], v[60:63], v[44:47], v[132:135]
	s_waitcnt vmcnt(6)
	s_barrier
	s_add_i32 m0, s32, 0
	s_nop 0
	global_load_lds_dwordx4 v64, s[4:5]
	s_add_i32 m0, s33, 0
	s_nop 0
	global_load_lds_dwordx4 v65, s[6:7]
	s_add_i32 m0, s33, 1024
	s_nop 0
	global_load_lds_dwordx4 v66, s[6:7]
	s_add_u32 s4, s4, 0x80
	s_addc_u32 s5, s5, 0
	s_add_u32 s6, s6, 0x80
	s_addc_u32 s7, s7, 0
	ds_read_b128 v[48:51], v68 offset:24576
	ds_read_b128 v[56:59], v68 offset:26624
	ds_read_b128 v[32:35], v67 offset:24576
	ds_read_b128 v[40:43], v67 offset:26624
	ds_read_b128 v[52:55], v68 offset:25600
	ds_read_b128 v[60:63], v68 offset:27648
	ds_read_b128 v[36:39], v67 offset:25600
	ds_read_b128 v[44:47], v67 offset:27648
	s_waitcnt lgkmcnt(4)
	v_mfma_f32_16x16x32_bf16 v[120:123], v[48:51], v[32:35], v[120:123]
	v_mfma_f32_16x16x32_bf16 v[124:127], v[56:59], v[32:35], v[124:127]
	v_mfma_f32_16x16x32_bf16 v[128:131], v[48:51], v[40:43], v[128:131]
	v_mfma_f32_16x16x32_bf16 v[132:135], v[56:59], v[40:43], v[132:135]
	s_waitcnt lgkmcnt(0)
	v_mfma_f32_16x16x32_bf16 v[120:123], v[52:55], v[36:39], v[120:123]
	v_mfma_f32_16x16x32_bf16 v[124:127], v[60:63], v[36:39], v[124:127]
	v_mfma_f32_16x16x32_bf16 v[128:131], v[52:55], v[44:47], v[128:131]
	v_mfma_f32_16x16x32_bf16 v[132:135], v[60:63], v[44:47], v[132:135]
	s_waitcnt vmcnt(6)
	s_barrier
	s_add_i32 m0, s32, 24576
	s_nop 0
	global_load_lds_dwordx4 v64, s[4:5]
	s_add_i32 m0, s33, 24576
	s_nop 0
	global_load_lds_dwordx4 v65, s[6:7]
	s_add_i32 m0, s33, 25600
	s_nop 0
	global_load_lds_dwordx4 v66, s[6:7]
	s_add_u32 s4, s4, 0x80
	s_addc_u32 s5, s5, 0
	s_add_u32 s6, s6, 0x80
	s_addc_u32 s7, s7, 0
	ds_read_b128 v[48:51], v70 offset:0
	ds_read_b128 v[56:59], v70 offset:2048
	ds_read_b128 v[32:35], v69 offset:0
	ds_read_b128 v[40:43], v69 offset:2048
	ds_read_b128 v[52:55], v70 offset:1024
	ds_read_b128 v[60:63], v70 offset:3072
	ds_read_b128 v[36:39], v69 offset:1024
	ds_read_b128 v[44:47], v69 offset:3072
	s_waitcnt lgkmcnt(4)
	v_mfma_f32_16x16x32_bf16 v[120:123], v[48:51], v[32:35], v[120:123]
	v_mfma_f32_16x16x32_bf16 v[124:127], v[56:59], v[32:35], v[124:127]
	v_mfma_f32_16x16x32_bf16 v[128:131], v[48:51], v[40:43], v[128:131]
	v_mfma_f32_16x16x32_bf16 v[132:135], v[56:59], v[40:43], v[132:135]
	s_waitcnt lgkmcnt(0)
	v_mfma_f32_16x16x32_bf16 v[120:123], v[52:55], v[36:39], v[120:123]
	v_mfma_f32_16x16x32_bf16 v[124:127], v[60:63], v[36:39], v[124:127]
	v_mfma_f32_16x16x32_bf16 v[128:131], v[52:55], v[44:47], v[128:131]
	v_mfma_f32_16x16x32_bf16 v[132:135], v[60:63], v[44:47], v[132:135]
	s_waitcnt vmcnt(6)
	s_barrier
	s_add_i32 m0, s32, 49152
	s_nop 0
	global_load_lds_dwordx4 v64, s[4:5]
	s_add_i32 m0, s33, 49152
	s_nop 0
	global_load_lds_dwordx4 v65, s[6:7]
	s_add_i32 m0, s33, 50176
	s_nop 0
	global_load_lds_dwordx4 v66, s[6:7]
	s_add_u32 s4, s4, 0x80
	s_addc_u32 s5, s5, 0
	s_add_u32 s6, s6, 0x80
	s_addc_u32 s7, s7, 0
	ds_read_b128 v[48:51], v70 offset:24576
	ds_read_b128 v[56:59], v70 offset:26624
	ds_read_b128 v[32:35], v69 offset:24576
	ds_read_b128 v[40:43], v69 offset:26624
	ds_read_b128 v[52:55], v70 offset:25600
	ds_read_b128 v[60:63], v70 offset:27648
	ds_read_b128 v[36:39], v69 offset:25600
	ds_read_b128 v[44:47], v69 offset:27648
	s_waitcnt lgkmcnt(4)
	v_mfma_f32_16x16x32_bf16 v[120:123], v[48:51], v[32:35], v[120:123]
	v_mfma_f32_16x16x32_bf16 v[124:127], v[56:59], v[32:35], v[124:127]
	v_mfma_f32_16x16x32_bf16 v[128:131], v[48:51], v[40:43], v[128:131]
	v_mfma_f32_16x16x32_bf16 v[132:135], v[56:59], v[40:43], v[132:135]
	s_waitcnt lgkmcnt(0)
	v_mfma_f32_16x16x32_bf16 v[120:123], v[52:55], v[36:39], v[120:123]
	v_mfma_f32_16x16x32_bf16 v[124:127], v[60:63], v[36:39], v[124:127]
	v_mfma_f32_16x16x32_bf16 v[128:131], v[52:55], v[44:47], v[128:131]
	v_mfma_f32_16x16x32_bf16 v[132:135], v[60:63], v[44:47], v[132:135]
	s_waitcnt vmcnt(6)
	s_barrier
	s_add_i32 m0, s32, 73728
	s_nop 0
	global_load_lds_dwordx4 v64, s[4:5]
	s_add_i32 m0, s33, 73728
	s_nop 0
	global_load_lds_dwordx4 v65, s[6:7]
	s_add_i32 m0, s33, 74752
	s_nop 0
	global_load_lds_dwordx4 v66, s[6:7]
	s_add_u32 s4, s4, 0x80
	s_addc_u32 s5, s5, 0
	s_add_u32 s6, s6, 0x80
	s_addc_u32 s7, s7, 0
	ds_read_b128 v[48:51], v68 offset:0
	ds_read_b128 v[56:59], v68 offset:2048
	ds_read_b128 v[32:35], v67 offset:0
	ds_read_b128 v[40:43], v67 offset:2048
	ds_read_b128 v[52:55], v68 offset:1024
	ds_read_b128 v[60:63], v68 offset:3072
	ds_read_b128 v[36:39], v67 offset:1024
	ds_read_b128 v[44:47], v67 offset:3072
	s_waitcnt lgkmcnt(4)
	v_mfma_f32_16x16x32_bf16 v[136:139], v[48:51], v[32:35], v[136:139]
	v_mfma_f32_16x16x32_bf16 v[140:143], v[56:59], v[32:35], v[140:143]
	v_mfma_f32_16x16x32_bf16 v[144:147], v[48:51], v[40:43], v[144:147]
	v_mfma_f32_16x16x32_bf16 v[148:151], v[56:59], v[40:43], v[148:151]
	s_waitcnt lgkmcnt(0)
	v_mfma_f32_16x16x32_bf16 v[136:139], v[52:55], v[36:39], v[136:139]
	v_mfma_f32_16x16x32_bf16 v[140:143], v[60:63], v[36:39], v[140:143]
	v_mfma_f32_16x16x32_bf16 v[144:147], v[52:55], v[44:47], v[144:147]
	v_mfma_f32_16x16x32_bf16 v[148:151], v[60:63], v[44:47], v[148:151]
	s_waitcnt vmcnt(6)
	s_barrier
	ds_read_b128 v[48:51], v68 offset:24576
	ds_read_b128 v[56:59], v68 offset:26624
	ds_read_b128 v[32:35], v67 offset:24576
	ds_read_b128 v[40:43], v67 offset:26624
	ds_read_b128 v[52:55], v68 offset:25600
	ds_read_b128 v[60:63], v68 offset:27648
	ds_read_b128 v[36:39], v67 offset:25600
	ds_read_b128 v[44:47], v67 offset:27648
	s_waitcnt lgkmcnt(4)
	v_mfma_f32_16x16x32_bf16 v[136:139], v[48:51], v[32:35], v[136:139]
	v_mfma_f32_16x16x32_bf16 v[140:143], v[56:59], v[32:35], v[140:143]
	v_mfma_f32_16x16x32_bf16 v[144:147], v[48:51], v[40:43], v[144:147]
	v_mfma_f32_16x16x32_bf16 v[148:151], v[56:59], v[40:43], v[148:151]
	s_waitcnt lgkmcnt(0)
	v_mfma_f32_16x16x32_bf16 v[136:139], v[52:55], v[36:39], v[136:139]
	v_mfma_f32_16x16x32_bf16 v[140:143], v[60:63], v[36:39], v[140:143]
	v_mfma_f32_16x16x32_bf16 v[144:147], v[52:55], v[44:47], v[144:147]
	v_mfma_f32_16x16x32_bf16 v[148:151], v[60:63], v[44:47], v[148:151]
	s_waitcnt vmcnt(3)
	s_barrier
	ds_read_b128 v[48:51], v70 offset:0
	ds_read_b128 v[56:59], v70 offset:2048
	ds_read_b128 v[32:35], v69 offset:0
	ds_read_b128 v[40:43], v69 offset:2048
	ds_read_b128 v[52:55], v70 offset:1024
	ds_read_b128 v[60:63], v70 offset:3072
	ds_read_b128 v[36:39], v69 offset:1024
	ds_read_b128 v[44:47], v69 offset:3072
	s_waitcnt lgkmcnt(4)
	v_mfma_f32_16x16x32_bf16 v[136:139], v[48:51], v[32:35], v[136:139]
	v_mfma_f32_16x16x32_bf16 v[140:143], v[56:59], v[32:35], v[140:143]
	v_mfma_f32_16x16x32_bf16 v[144:147], v[48:51], v[40:43], v[144:147]
	v_mfma_f32_16x16x32_bf16 v[148:151], v[56:59], v[40:43], v[148:151]
	s_waitcnt lgkmcnt(0)
	v_mfma_f32_16x16x32_bf16 v[136:139], v[52:55], v[36:39], v[136:139]
	v_mfma_f32_16x16x32_bf16 v[140:143], v[60:63], v[36:39], v[140:143]
	v_mfma_f32_16x16x32_bf16 v[144:147], v[52:55], v[44:47], v[144:147]
	v_mfma_f32_16x16x32_bf16 v[148:151], v[60:63], v[44:47], v[148:151]
	s_waitcnt vmcnt(0)
	s_barrier
	ds_read_b128 v[48:51], v70 offset:24576
	ds_read_b128 v[56:59], v70 offset:26624
	ds_read_b128 v[32:35], v69 offset:24576
	ds_read_b128 v[40:43], v69 offset:26624
	ds_read_b128 v[52:55], v70 offset:25600
	ds_read_b128 v[60:63], v70 offset:27648
	ds_read_b128 v[36:39], v69 offset:25600
	ds_read_b128 v[44:47], v69 offset:27648
	s_waitcnt lgkmcnt(4)
	v_mfma_f32_16x16x32_bf16 v[136:139], v[48:51], v[32:35], v[136:139]
	v_mfma_f32_16x16x32_bf16 v[140:143], v[56:59], v[32:35], v[140:143]
	v_mfma_f32_16x16x32_bf16 v[144:147], v[48:51], v[40:43], v[144:147]
	v_mfma_f32_16x16x32_bf16 v[148:151], v[56:59], v[40:43], v[148:151]
	s_waitcnt lgkmcnt(0)
	v_mfma_f32_16x16x32_bf16 v[136:139], v[52:55], v[36:39], v[136:139]
	v_mfma_f32_16x16x32_bf16 v[140:143], v[60:63], v[36:39], v[140:143]
	v_mfma_f32_16x16x32_bf16 v[144:147], v[52:55], v[44:47], v[144:147]
	v_mfma_f32_16x16x32_bf16 v[148:151], v[60:63], v[44:47], v[148:151]
	s_nop 7
	s_nop 1
	v_lshlrev_b32_e32 v48, 16, v168
	v_and_b32_e32 v49, 0xffff0000, v168
	v_lshlrev_b32_e32 v50, 16, v169
	v_and_b32_e32 v51, 0xffff0000, v169
	v_lshlrev_b32_e32 v52, 16, v176
	v_and_b32_e32 v53, 0xffff0000, v176
	v_lshlrev_b32_e32 v54, 16, v177
	v_and_b32_e32 v55, 0xffff0000, v177
	v_lshlrev_b32_e32 v56, 16, v184
	v_and_b32_e32 v57, 0xffff0000, v184
	v_lshlrev_b32_e32 v58, 16, v185
	v_and_b32_e32 v59, 0xffff0000, v185
	v_lshlrev_b32_e32 v60, 16, v192
	v_and_b32_e32 v61, 0xffff0000, v192
	v_lshlrev_b32_e32 v62, 16, v193
	v_and_b32_e32 v63, 0xffff0000, v193
	v_add_f32_e32 v48, v48, v72
	v_add_f32_e32 v49, v49, v73
	v_add_f32_e32 v50, v50, v74
	v_add_f32_e32 v51, v51, v75
	v_add_f32_e32 v52, v52, v80
	v_add_f32_e32 v53, v53, v81
	v_add_f32_e32 v54, v54, v82
	v_add_f32_e32 v55, v55, v83
	v_add_f32_e32 v56, v56, v88
	v_add_f32_e32 v57, v57, v89
	v_add_f32_e32 v58, v58, v90
	v_add_f32_e32 v59, v59, v91
	v_add_f32_e32 v60, v60, v96
	v_add_f32_e32 v61, v61, v97
	v_add_f32_e32 v62, v62, v98
	v_add_f32_e32 v63, v63, v99
	v_mul_f32_e32 v48, 0xbfb8aa3b, v48
	v_mul_f32_e32 v49, 0xbfb8aa3b, v49
	v_mul_f32_e32 v50, 0xbfb8aa3b, v50
	v_mul_f32_e32 v51, 0xbfb8aa3b, v51
	v_mul_f32_e32 v52, 0xbfb8aa3b, v52
	v_mul_f32_e32 v53, 0xbfb8aa3b, v53
	v_mul_f32_e32 v54, 0xbfb8aa3b, v54
	v_mul_f32_e32 v55, 0xbfb8aa3b, v55
	v_mul_f32_e32 v56, 0xbfb8aa3b, v56
	v_mul_f32_e32 v57, 0xbfb8aa3b, v57
	v_mul_f32_e32 v58, 0xbfb8aa3b, v58
	v_mul_f32_e32 v59, 0xbfb8aa3b, v59
	v_mul_f32_e32 v60, 0xbfb8aa3b, v60
	v_mul_f32_e32 v61, 0xbfb8aa3b, v61
	v_mul_f32_e32 v62, 0xbfb8aa3b, v62
	v_mul_f32_e32 v63, 0xbfb8aa3b, v63
	v_exp_f32_e32 v48, v48
	v_exp_f32_e32 v49, v49
	v_exp_f32_e32 v50, v50
	v_exp_f32_e32 v51, v51
	v_exp_f32_e32 v52, v52
	v_exp_f32_e32 v53, v53
	v_exp_f32_e32 v54, v54
	v_exp_f32_e32 v55, v55
	v_exp_f32_e32 v56, v56
	v_exp_f32_e32 v57, v57
	v_exp_f32_e32 v58, v58
	v_exp_f32_e32 v59, v59
	v_exp_f32_e32 v60, v60
	v_exp_f32_e32 v61, v61
	v_exp_f32_e32 v62, v62
	v_exp_f32_e32 v63, v63
	v_min_f32_e32 v48, 0x60ad78ec, v48
	v_min_f32_e32 v49, 0x60ad78ec, v49
	v_min_f32_e32 v50, 0x60ad78ec, v50
	v_min_f32_e32 v51, 0x60ad78ec, v51
	v_min_f32_e32 v52, 0x60ad78ec, v52
	v_min_f32_e32 v53, 0x60ad78ec, v53
	v_min_f32_e32 v54, 0x60ad78ec, v54
	v_min_f32_e32 v55, 0x60ad78ec, v55
	v_min_f32_e32 v56, 0x60ad78ec, v56
	v_min_f32_e32 v57, 0x60ad78ec, v57
	v_min_f32_e32 v58, 0x60ad78ec, v58
	v_min_f32_e32 v59, 0x60ad78ec, v59
	v_min_f32_e32 v60, 0x60ad78ec, v60
	v_min_f32_e32 v61, 0x60ad78ec, v61
	v_min_f32_e32 v62, 0x60ad78ec, v62
	v_min_f32_e32 v63, 0x60ad78ec, v63
	v_add_f32_e32 v48, 1.0, v48
	v_add_f32_e32 v49, 1.0, v49
	v_add_f32_e32 v50, 1.0, v50
	v_add_f32_e32 v51, 1.0, v51
	v_add_f32_e32 v52, 1.0, v52
	v_add_f32_e32 v53, 1.0, v53
	v_add_f32_e32 v54, 1.0, v54
	v_add_f32_e32 v55, 1.0, v55
	v_add_f32_e32 v56, 1.0, v56
	v_add_f32_e32 v57, 1.0, v57
	v_add_f32_e32 v58, 1.0, v58
	v_add_f32_e32 v59, 1.0, v59
	v_add_f32_e32 v60, 1.0, v60
	v_add_f32_e32 v61, 1.0, v61
	v_add_f32_e32 v62, 1.0, v62
	v_add_f32_e32 v63, 1.0, v63
	v_rcp_f32_e32 v48, v48
	v_rcp_f32_e32 v49, v49
	v_rcp_f32_e32 v50, v50
	v_rcp_f32_e32 v51, v51
	v_rcp_f32_e32 v52, v52
	v_rcp_f32_e32 v53, v53
	v_rcp_f32_e32 v54, v54
	v_rcp_f32_e32 v55, v55
	v_rcp_f32_e32 v56, v56
	v_rcp_f32_e32 v57, v57
	v_rcp_f32_e32 v58, v58
	v_rcp_f32_e32 v59, v59
	v_rcp_f32_e32 v60, v60
	v_rcp_f32_e32 v61, v61
	v_rcp_f32_e32 v62, v62
	v_rcp_f32_e32 v63, v63
	v_mul_f32_e32 v32, v48, v16
	v_mul_f32_e32 v33, v49, v17
	v_mul_f32_e32 v34, v50, v18
	v_mul_f32_e32 v35, v51, v19
	v_fmac_f32_e32 v32, v52, v104
	v_fmac_f32_e32 v33, v53, v105
	v_fmac_f32_e32 v34, v54, v106
	v_fmac_f32_e32 v35, v55, v107
	v_fmac_f32_e32 v32, v56, v120
	v_fmac_f32_e32 v33, v57, v121
	v_fmac_f32_e32 v34, v58, v122
	v_fmac_f32_e32 v35, v59, v123
	v_fmac_f32_e32 v32, v60, v136
	v_fmac_f32_e32 v33, v61, v137
	v_fmac_f32_e32 v34, v62, v138
	v_fmac_f32_e32 v35, v63, v139
	v_lshlrev_b32_e32 v48, 16, v170
	v_and_b32_e32 v49, 0xffff0000, v170
	v_lshlrev_b32_e32 v50, 16, v171
	v_and_b32_e32 v51, 0xffff0000, v171
	v_lshlrev_b32_e32 v52, 16, v178
	v_and_b32_e32 v53, 0xffff0000, v178
	v_lshlrev_b32_e32 v54, 16, v179
	v_and_b32_e32 v55, 0xffff0000, v179
	v_lshlrev_b32_e32 v56, 16, v186
	v_and_b32_e32 v57, 0xffff0000, v186
	v_lshlrev_b32_e32 v58, 16, v187
	v_and_b32_e32 v59, 0xffff0000, v187
	v_lshlrev_b32_e32 v60, 16, v194
	v_and_b32_e32 v61, 0xffff0000, v194
	v_lshlrev_b32_e32 v62, 16, v195
	v_and_b32_e32 v63, 0xffff0000, v195
	v_add_f32_e32 v48, v48, v76
	v_add_f32_e32 v49, v49, v77
	v_add_f32_e32 v50, v50, v78
	v_add_f32_e32 v51, v51, v79
	v_add_f32_e32 v52, v52, v84
	v_add_f32_e32 v53, v53, v85
	v_add_f32_e32 v54, v54, v86
	v_add_f32_e32 v55, v55, v87
	v_add_f32_e32 v56, v56, v92
	v_add_f32_e32 v57, v57, v93
	v_add_f32_e32 v58, v58, v94
	v_add_f32_e32 v59, v59, v95
	v_add_f32_e32 v60, v60, v100
	v_add_f32_e32 v61, v61, v101
	v_add_f32_e32 v62, v62, v102
	v_add_f32_e32 v63, v63, v103
	v_mul_f32_e32 v48, 0xbfb8aa3b, v48
	v_mul_f32_e32 v49, 0xbfb8aa3b, v49
	v_mul_f32_e32 v50, 0xbfb8aa3b, v50
	v_mul_f32_e32 v51, 0xbfb8aa3b, v51
	v_mul_f32_e32 v52, 0xbfb8aa3b, v52
	v_mul_f32_e32 v53, 0xbfb8aa3b, v53
	v_mul_f32_e32 v54, 0xbfb8aa3b, v54
	v_mul_f32_e32 v55, 0xbfb8aa3b, v55
	v_mul_f32_e32 v56, 0xbfb8aa3b, v56
	v_mul_f32_e32 v57, 0xbfb8aa3b, v57
	v_mul_f32_e32 v58, 0xbfb8aa3b, v58
	v_mul_f32_e32 v59, 0xbfb8aa3b, v59
	v_mul_f32_e32 v60, 0xbfb8aa3b, v60
	v_mul_f32_e32 v61, 0xbfb8aa3b, v61
	v_mul_f32_e32 v62, 0xbfb8aa3b, v62
	v_mul_f32_e32 v63, 0xbfb8aa3b, v63
	v_exp_f32_e32 v48, v48
	v_exp_f32_e32 v49, v49
	v_exp_f32_e32 v50, v50
	v_exp_f32_e32 v51, v51
	v_exp_f32_e32 v52, v52
	v_exp_f32_e32 v53, v53
	v_exp_f32_e32 v54, v54
	v_exp_f32_e32 v55, v55
	v_exp_f32_e32 v56, v56
	v_exp_f32_e32 v57, v57
	v_exp_f32_e32 v58, v58
	v_exp_f32_e32 v59, v59
	v_exp_f32_e32 v60, v60
	v_exp_f32_e32 v61, v61
	v_exp_f32_e32 v62, v62
	v_exp_f32_e32 v63, v63
	v_min_f32_e32 v48, 0x60ad78ec, v48
	v_min_f32_e32 v49, 0x60ad78ec, v49
	v_min_f32_e32 v50, 0x60ad78ec, v50
	v_min_f32_e32 v51, 0x60ad78ec, v51
	v_min_f32_e32 v52, 0x60ad78ec, v52
	v_min_f32_e32 v53, 0x60ad78ec, v53
	v_min_f32_e32 v54, 0x60ad78ec, v54
	v_min_f32_e32 v55, 0x60ad78ec, v55
	v_min_f32_e32 v56, 0x60ad78ec, v56
	v_min_f32_e32 v57, 0x60ad78ec, v57
	v_min_f32_e32 v58, 0x60ad78ec, v58
	v_min_f32_e32 v59, 0x60ad78ec, v59
	v_min_f32_e32 v60, 0x60ad78ec, v60
	v_min_f32_e32 v61, 0x60ad78ec, v61
	v_min_f32_e32 v62, 0x60ad78ec, v62
	v_min_f32_e32 v63, 0x60ad78ec, v63
	v_add_f32_e32 v48, 1.0, v48
	v_add_f32_e32 v49, 1.0, v49
	v_add_f32_e32 v50, 1.0, v50
	v_add_f32_e32 v51, 1.0, v51
	v_add_f32_e32 v52, 1.0, v52
	v_add_f32_e32 v53, 1.0, v53
	v_add_f32_e32 v54, 1.0, v54
	v_add_f32_e32 v55, 1.0, v55
	v_add_f32_e32 v56, 1.0, v56
	v_add_f32_e32 v57, 1.0, v57
	v_add_f32_e32 v58, 1.0, v58
	v_add_f32_e32 v59, 1.0, v59
	v_add_f32_e32 v60, 1.0, v60
	v_add_f32_e32 v61, 1.0, v61
	v_add_f32_e32 v62, 1.0, v62
	v_add_f32_e32 v63, 1.0, v63
	v_rcp_f32_e32 v48, v48
	v_rcp_f32_e32 v49, v49
	v_rcp_f32_e32 v50, v50
	v_rcp_f32_e32 v51, v51
	v_rcp_f32_e32 v52, v52
	v_rcp_f32_e32 v53, v53
	v_rcp_f32_e32 v54, v54
	v_rcp_f32_e32 v55, v55
	v_rcp_f32_e32 v56, v56
	v_rcp_f32_e32 v57, v57
	v_rcp_f32_e32 v58, v58
	v_rcp_f32_e32 v59, v59
	v_rcp_f32_e32 v60, v60
	v_rcp_f32_e32 v61, v61
	v_rcp_f32_e32 v62, v62
	v_rcp_f32_e32 v63, v63
	v_mul_f32_e32 v36, v48, v20
	v_mul_f32_e32 v37, v49, v21
	v_mul_f32_e32 v38, v50, v22
	v_mul_f32_e32 v39, v51, v23
	v_fmac_f32_e32 v36, v52, v108
	v_fmac_f32_e32 v37, v53, v109
	v_fmac_f32_e32 v38, v54, v110
	v_fmac_f32_e32 v39, v55, v111
	v_fmac_f32_e32 v36, v56, v124
	v_fmac_f32_e32 v37, v57, v125
	v_fmac_f32_e32 v38, v58, v126
	v_fmac_f32_e32 v39, v59, v127
	v_fmac_f32_e32 v36, v60, v140
	v_fmac_f32_e32 v37, v61, v141
	v_fmac_f32_e32 v38, v62, v142
	v_fmac_f32_e32 v39, v63, v143
	v_lshlrev_b32_e32 v48, 16, v172
	v_and_b32_e32 v49, 0xffff0000, v172
	v_lshlrev_b32_e32 v50, 16, v173
	v_and_b32_e32 v51, 0xffff0000, v173
	v_lshlrev_b32_e32 v52, 16, v180
	v_and_b32_e32 v53, 0xffff0000, v180
	v_lshlrev_b32_e32 v54, 16, v181
	v_and_b32_e32 v55, 0xffff0000, v181
	v_lshlrev_b32_e32 v56, 16, v188
	v_and_b32_e32 v57, 0xffff0000, v188
	v_lshlrev_b32_e32 v58, 16, v189
	v_and_b32_e32 v59, 0xffff0000, v189
	v_lshlrev_b32_e32 v60, 16, v196
	v_and_b32_e32 v61, 0xffff0000, v196
	v_lshlrev_b32_e32 v62, 16, v197
	v_and_b32_e32 v63, 0xffff0000, v197
	v_add_f32_e32 v48, v48, v72
	v_add_f32_e32 v49, v49, v73
	v_add_f32_e32 v50, v50, v74
	v_add_f32_e32 v51, v51, v75
	v_add_f32_e32 v52, v52, v80
	v_add_f32_e32 v53, v53, v81
	v_add_f32_e32 v54, v54, v82
	v_add_f32_e32 v55, v55, v83
	v_add_f32_e32 v56, v56, v88
	v_add_f32_e32 v57, v57, v89
	v_add_f32_e32 v58, v58, v90
	v_add_f32_e32 v59, v59, v91
	v_add_f32_e32 v60, v60, v96
	v_add_f32_e32 v61, v61, v97
	v_add_f32_e32 v62, v62, v98
	v_add_f32_e32 v63, v63, v99
	v_mul_f32_e32 v48, 0xbfb8aa3b, v48
	v_mul_f32_e32 v49, 0xbfb8aa3b, v49
	v_mul_f32_e32 v50, 0xbfb8aa3b, v50
	v_mul_f32_e32 v51, 0xbfb8aa3b, v51
	v_mul_f32_e32 v52, 0xbfb8aa3b, v52
	v_mul_f32_e32 v53, 0xbfb8aa3b, v53
	v_mul_f32_e32 v54, 0xbfb8aa3b, v54
	v_mul_f32_e32 v55, 0xbfb8aa3b, v55
	v_mul_f32_e32 v56, 0xbfb8aa3b, v56
	v_mul_f32_e32 v57, 0xbfb8aa3b, v57
	v_mul_f32_e32 v58, 0xbfb8aa3b, v58
	v_mul_f32_e32 v59, 0xbfb8aa3b, v59
	v_mul_f32_e32 v60, 0xbfb8aa3b, v60
	v_mul_f32_e32 v61, 0xbfb8aa3b, v61
	v_mul_f32_e32 v62, 0xbfb8aa3b, v62
	v_mul_f32_e32 v63, 0xbfb8aa3b, v63
	v_exp_f32_e32 v48, v48
	v_exp_f32_e32 v49, v49
	v_exp_f32_e32 v50, v50
	v_exp_f32_e32 v51, v51
	v_exp_f32_e32 v52, v52
	v_exp_f32_e32 v53, v53
	v_exp_f32_e32 v54, v54
	v_exp_f32_e32 v55, v55
	v_exp_f32_e32 v56, v56
	v_exp_f32_e32 v57, v57
	v_exp_f32_e32 v58, v58
	v_exp_f32_e32 v59, v59
	v_exp_f32_e32 v60, v60
	v_exp_f32_e32 v61, v61
	v_exp_f32_e32 v62, v62
	v_exp_f32_e32 v63, v63
	v_min_f32_e32 v48, 0x60ad78ec, v48
	v_min_f32_e32 v49, 0x60ad78ec, v49
	v_min_f32_e32 v50, 0x60ad78ec, v50
	v_min_f32_e32 v51, 0x60ad78ec, v51
	v_min_f32_e32 v52, 0x60ad78ec, v52
	v_min_f32_e32 v53, 0x60ad78ec, v53
	v_min_f32_e32 v54, 0x60ad78ec, v54
	v_min_f32_e32 v55, 0x60ad78ec, v55
	v_min_f32_e32 v56, 0x60ad78ec, v56
	v_min_f32_e32 v57, 0x60ad78ec, v57
	v_min_f32_e32 v58, 0x60ad78ec, v58
	v_min_f32_e32 v59, 0x60ad78ec, v59
	v_min_f32_e32 v60, 0x60ad78ec, v60
	v_min_f32_e32 v61, 0x60ad78ec, v61
	v_min_f32_e32 v62, 0x60ad78ec, v62
	v_min_f32_e32 v63, 0x60ad78ec, v63
	v_add_f32_e32 v48, 1.0, v48
	v_add_f32_e32 v49, 1.0, v49
	v_add_f32_e32 v50, 1.0, v50
	v_add_f32_e32 v51, 1.0, v51
	v_add_f32_e32 v52, 1.0, v52
	v_add_f32_e32 v53, 1.0, v53
	v_add_f32_e32 v54, 1.0, v54
	v_add_f32_e32 v55, 1.0, v55
	v_add_f32_e32 v56, 1.0, v56
	v_add_f32_e32 v57, 1.0, v57
	v_add_f32_e32 v58, 1.0, v58
	v_add_f32_e32 v59, 1.0, v59
	v_add_f32_e32 v60, 1.0, v60
	v_add_f32_e32 v61, 1.0, v61
	v_add_f32_e32 v62, 1.0, v62
	v_add_f32_e32 v63, 1.0, v63
	v_rcp_f32_e32 v48, v48
	v_rcp_f32_e32 v49, v49
	v_rcp_f32_e32 v50, v50
	v_rcp_f32_e32 v51, v51
	v_rcp_f32_e32 v52, v52
	v_rcp_f32_e32 v53, v53
	v_rcp_f32_e32 v54, v54
	v_rcp_f32_e32 v55, v55
	v_rcp_f32_e32 v56, v56
	v_rcp_f32_e32 v57, v57
	v_rcp_f32_e32 v58, v58
	v_rcp_f32_e32 v59, v59
	v_rcp_f32_e32 v60, v60
	v_rcp_f32_e32 v61, v61
	v_rcp_f32_e32 v62, v62
	v_rcp_f32_e32 v63, v63
	v_mul_f32_e32 v40, v48, v24
	v_mul_f32_e32 v41, v49, v25
	v_mul_f32_e32 v42, v50, v26
	v_mul_f32_e32 v43, v51, v27
	v_fmac_f32_e32 v40, v52, v112
	v_fmac_f32_e32 v41, v53, v113
	v_fmac_f32_e32 v42, v54, v114
	v_fmac_f32_e32 v43, v55, v115
	v_fmac_f32_e32 v40, v56, v128
	v_fmac_f32_e32 v41, v57, v129
	v_fmac_f32_e32 v42, v58, v130
	v_fmac_f32_e32 v43, v59, v131
	v_fmac_f32_e32 v40, v60, v144
	v_fmac_f32_e32 v41, v61, v145
	v_fmac_f32_e32 v42, v62, v146
	v_fmac_f32_e32 v43, v63, v147
	v_lshlrev_b32_e32 v48, 16, v174
	v_and_b32_e32 v49, 0xffff0000, v174
	v_lshlrev_b32_e32 v50, 16, v175
	v_and_b32_e32 v51, 0xffff0000, v175
	v_lshlrev_b32_e32 v52, 16, v182
	v_and_b32_e32 v53, 0xffff0000, v182
	v_lshlrev_b32_e32 v54, 16, v183
	v_and_b32_e32 v55, 0xffff0000, v183
	v_lshlrev_b32_e32 v56, 16, v190
	v_and_b32_e32 v57, 0xffff0000, v190
	v_lshlrev_b32_e32 v58, 16, v191
	v_and_b32_e32 v59, 0xffff0000, v191
	v_lshlrev_b32_e32 v60, 16, v198
	v_and_b32_e32 v61, 0xffff0000, v198
	v_lshlrev_b32_e32 v62, 16, v199
	v_and_b32_e32 v63, 0xffff0000, v199
	v_add_f32_e32 v48, v48, v76
	v_add_f32_e32 v49, v49, v77
	v_add_f32_e32 v50, v50, v78
	v_add_f32_e32 v51, v51, v79
	v_add_f32_e32 v52, v52, v84
	v_add_f32_e32 v53, v53, v85
	v_add_f32_e32 v54, v54, v86
	v_add_f32_e32 v55, v55, v87
	v_add_f32_e32 v56, v56, v92
	v_add_f32_e32 v57, v57, v93
	v_add_f32_e32 v58, v58, v94
	v_add_f32_e32 v59, v59, v95
	v_add_f32_e32 v60, v60, v100
	v_add_f32_e32 v61, v61, v101
	v_add_f32_e32 v62, v62, v102
	v_add_f32_e32 v63, v63, v103
	v_mul_f32_e32 v48, 0xbfb8aa3b, v48
	v_mul_f32_e32 v49, 0xbfb8aa3b, v49
	v_mul_f32_e32 v50, 0xbfb8aa3b, v50
	v_mul_f32_e32 v51, 0xbfb8aa3b, v51
	v_mul_f32_e32 v52, 0xbfb8aa3b, v52
	v_mul_f32_e32 v53, 0xbfb8aa3b, v53
	v_mul_f32_e32 v54, 0xbfb8aa3b, v54
	v_mul_f32_e32 v55, 0xbfb8aa3b, v55
	v_mul_f32_e32 v56, 0xbfb8aa3b, v56
	v_mul_f32_e32 v57, 0xbfb8aa3b, v57
	v_mul_f32_e32 v58, 0xbfb8aa3b, v58
	v_mul_f32_e32 v59, 0xbfb8aa3b, v59
	v_mul_f32_e32 v60, 0xbfb8aa3b, v60
	v_mul_f32_e32 v61, 0xbfb8aa3b, v61
	v_mul_f32_e32 v62, 0xbfb8aa3b, v62
	v_mul_f32_e32 v63, 0xbfb8aa3b, v63
	v_exp_f32_e32 v48, v48
	v_exp_f32_e32 v49, v49
	v_exp_f32_e32 v50, v50
	v_exp_f32_e32 v51, v51
	v_exp_f32_e32 v52, v52
	v_exp_f32_e32 v53, v53
	v_exp_f32_e32 v54, v54
	v_exp_f32_e32 v55, v55
	v_exp_f32_e32 v56, v56
	v_exp_f32_e32 v57, v57
	v_exp_f32_e32 v58, v58
	v_exp_f32_e32 v59, v59
	v_exp_f32_e32 v60, v60
	v_exp_f32_e32 v61, v61
	v_exp_f32_e32 v62, v62
	v_exp_f32_e32 v63, v63
	v_min_f32_e32 v48, 0x60ad78ec, v48
	v_min_f32_e32 v49, 0x60ad78ec, v49
	v_min_f32_e32 v50, 0x60ad78ec, v50
	v_min_f32_e32 v51, 0x60ad78ec, v51
	v_min_f32_e32 v52, 0x60ad78ec, v52
	v_min_f32_e32 v53, 0x60ad78ec, v53
	v_min_f32_e32 v54, 0x60ad78ec, v54
	v_min_f32_e32 v55, 0x60ad78ec, v55
	v_min_f32_e32 v56, 0x60ad78ec, v56
	v_min_f32_e32 v57, 0x60ad78ec, v57
	v_min_f32_e32 v58, 0x60ad78ec, v58
	v_min_f32_e32 v59, 0x60ad78ec, v59
	v_min_f32_e32 v60, 0x60ad78ec, v60
	v_min_f32_e32 v61, 0x60ad78ec, v61
	v_min_f32_e32 v62, 0x60ad78ec, v62
	v_min_f32_e32 v63, 0x60ad78ec, v63
	v_add_f32_e32 v48, 1.0, v48
	v_add_f32_e32 v49, 1.0, v49
	v_add_f32_e32 v50, 1.0, v50
	v_add_f32_e32 v51, 1.0, v51
	v_add_f32_e32 v52, 1.0, v52
	v_add_f32_e32 v53, 1.0, v53
	v_add_f32_e32 v54, 1.0, v54
	v_add_f32_e32 v55, 1.0, v55
	v_add_f32_e32 v56, 1.0, v56
	v_add_f32_e32 v57, 1.0, v57
	v_add_f32_e32 v58, 1.0, v58
	v_add_f32_e32 v59, 1.0, v59
	v_add_f32_e32 v60, 1.0, v60
	v_add_f32_e32 v61, 1.0, v61
	v_add_f32_e32 v62, 1.0, v62
	v_add_f32_e32 v63, 1.0, v63
	v_rcp_f32_e32 v48, v48
	v_rcp_f32_e32 v49, v49
	v_rcp_f32_e32 v50, v50
	v_rcp_f32_e32 v51, v51
	v_rcp_f32_e32 v52, v52
	v_rcp_f32_e32 v53, v53
	v_rcp_f32_e32 v54, v54
	v_rcp_f32_e32 v55, v55
	v_rcp_f32_e32 v56, v56
	v_rcp_f32_e32 v57, v57
	v_rcp_f32_e32 v58, v58
	v_rcp_f32_e32 v59, v59
	v_rcp_f32_e32 v60, v60
	v_rcp_f32_e32 v61, v61
	v_rcp_f32_e32 v62, v62
	v_rcp_f32_e32 v63, v63
	v_mul_f32_e32 v44, v48, v28
	v_mul_f32_e32 v45, v49, v29
	v_mul_f32_e32 v46, v50, v30
	v_mul_f32_e32 v47, v51, v31
	v_fmac_f32_e32 v44, v52, v116
	v_fmac_f32_e32 v45, v53, v117
	v_fmac_f32_e32 v46, v54, v118
	v_fmac_f32_e32 v47, v55, v119
	v_fmac_f32_e32 v44, v56, v132
	v_fmac_f32_e32 v45, v57, v133
	v_fmac_f32_e32 v46, v58, v134
	v_fmac_f32_e32 v47, v59, v135
	v_fmac_f32_e32 v44, v60, v148
	v_fmac_f32_e32 v45, v61, v149
	v_fmac_f32_e32 v46, v62, v150
	v_fmac_f32_e32 v47, v63, v151
	v_cvt_pk_bf16_f32 v48, v32, v33
	v_cvt_pk_bf16_f32 v49, v34, v35
	v_cvt_pk_bf16_f32 v50, v36, v37
	v_cvt_pk_bf16_f32 v51, v38, v39
	v_cvt_pk_bf16_f32 v52, v40, v41
	v_cvt_pk_bf16_f32 v53, v42, v43
	v_cvt_pk_bf16_f32 v54, v44, v45
	v_cvt_pk_bf16_f32 v55, v46, v47
	global_store_dwordx2 v203, v[48:49], s[58:59]
	global_store_dwordx2 v203, v[50:51], s[58:59] offset:32
	global_store_dwordx2 v204, v[52:53], s[58:59]
	global_store_dwordx2 v204, v[54:55], s[58:59] offset:32
	s_add_u32 s60, s60, 0x400000
	s_addc_u32 s61, s61, 0
	s_add_u32 s58, s58, 0x400000
	s_addc_u32 s59, s59, 0
	s_add_u32 s34, s34, 0x1800000
	s_addc_u32 s35, s35, 0
	s_add_u32 s15, s15, 1
	s_cmp_lt_u32 s15, s80
	s_cbranch_scc1 .Lsb_tile
	s_barrier
	s_branch .LBB0_1139
